# waves 4-7 run at s_setprio 1 for the whole kernel (GEMM phases too)
# speedup vs baseline: 1.0139x; 1.0023x over previous
; DI float siluf(float x) { return x / (1.f + __expf(-x)); }
; DI unsigned xb_add(unsigned* p, unsigned v) { return __hip_atomic_fetch_add(p, v, __ATOMIC_RELAXED, __HIP_MEMORY_SCOPE_AGENT); }
; DI unsigned xb_xcc_id() { return (unsigned)__builtin_amdgcn_s_getreg((3 << 11) | 20) & 0xFu; }
; #define PH(k, call) if (lo <= (k) && (k) < hi) { call; if ((k) + 1 < hi) GSYNC(); }
; DI void phase0(const Params& P, unsigned char* lds) {
;   const int tid = threadIdx.x;
;   float* fl = (float*)lds;
;   const int n_mod = 192, n_win = 16 * 56, n_wout = 256, n_wuq = 72, n_wukv = 64, n_l = 32;
;   const int total = n_mod + n_win + n_wout + n_wuq + n_wukv + n_l;
;   for (int it = blockIdx.x; it < total; it += gridDim.x) {
;     int r = it;
;     if (r < n_mod) {
;       __syncthreads();
;       for (int i = tid; i < 3072; i += NTHR) { int sidx = i >> 10, k = i & 1023; float cv = (sidx == 0) ? P.c[k] : (sidx == 1) ? P.c[1024 + k] : P.c_ctx[k]; fl[i] = siluf(cv); }
;       __syncthreads();
;       const int cl = tid & 15, kg = tid >> 4, n0 = r * 16;
;       float a0 = 0, a1 = 0, a2 = 0;
; #pragma unroll 8
;       for (int k = kg; k < 1024; k += 32) { float wv = P.ada_w[(size_t)k * 3072 + n0 + cl]; a0 += fl[k] * wv; a1 += fl[1024 + k] * wv; a2 += fl[2048 + k] * wv; }
;       __syncthreads();
;       fl[4096 + (kg * 3 + 0) * 16 + cl] = a0; fl[4096 + (kg * 3 + 1) * 16 + cl] = a1; fl[4096 + (kg * 3 + 2) * 16 + cl] = a2;
;       __syncthreads();
;       if (tid < 48) { int sidx = tid >> 4; float sum = 0; for (int qq = 0; qq < 32; ++qq) sum += fl[4096 + (qq * 3 + sidx) * 16 + cl];
;         ((float*)(P.ws + OFF_MOD))[sidx * 3072 + n0 + cl] = sum + P.ada_b[n0 + cl]; }
; __global__ void __launch_bounds__(NTHR) mega(Params P) {
;   __shared__ __attribute__((aligned(16))) unsigned char lds[LDS_BYTES];
;   const int lo = P.ph_lo, hi = P.ph_hi;
;   __shared__ unsigned bar_st[4];
;   if (threadIdx.x < 4) bar_st[threadIdx.x] = 0u;
;   __syncthreads();
;   XcdBarrier xbar; xbar.bar = (unsigned*)(P.ws + OFF_BAR); xbar.x = xb_xcc_id(); xbar.st = bar_st;
;   if (hi - lo > 1 && threadIdx.x == 0) (void)xb_add(&xbar.bar[XB_XCNT(xbar.x)], 1u);
;   if (lo < 0) cg::this_grid().sync();
;     ...
;   PH(0, phase0(P, lds))
.LBB0_17:
	s_load_dwordx16 s[60:75], s[78:79], 0x0
	s_load_dwordx16 s[0:15], s[78:79], 0x40
	s_cmp_lt_i32 s96, 1
	s_waitcnt lgkmcnt(0)
	v_writelane_b32 v243, s0, 2
	s_nop 1
	v_writelane_b32 v243, s1, 3
	v_writelane_b32 v243, s2, 4
	v_writelane_b32 v243, s3, 5
	v_writelane_b32 v243, s4, 6
	v_writelane_b32 v243, s5, 7
	v_writelane_b32 v243, s6, 8
	v_writelane_b32 v243, s7, 9
	v_writelane_b32 v243, s8, 10
	v_writelane_b32 v243, s9, 11
	v_writelane_b32 v243, s10, 12
	v_writelane_b32 v243, s11, 13
	v_writelane_b32 v243, s12, 14
	v_writelane_b32 v243, s13, 15
	v_writelane_b32 v243, s14, 16
	v_writelane_b32 v243, s15, 17
	s_load_dwordx16 s[0:15], s[78:79], 0x80
	s_waitcnt lgkmcnt(0)
	v_writelane_b32 v243, s0, 18
	s_nop 1
	v_writelane_b32 v243, s1, 19
	v_writelane_b32 v243, s2, 20
	v_writelane_b32 v243, s3, 21
	v_writelane_b32 v243, s4, 22
	v_writelane_b32 v243, s5, 23
	v_writelane_b32 v243, s6, 24
	v_writelane_b32 v243, s7, 25
	v_writelane_b32 v243, s8, 26
	v_writelane_b32 v243, s9, 27
	v_writelane_b32 v243, s10, 28
	v_writelane_b32 v243, s11, 29
	v_writelane_b32 v243, s12, 30
	v_writelane_b32 v243, s13, 31
	v_writelane_b32 v243, s14, 32
	v_writelane_b32 v243, s15, 33
	s_cselect_b64 s[0:1], -1, 0
	s_cmp_gt_i32 s97, 0
	s_cselect_b64 s[2:3], -1, 0
	s_and_b64 s[0:1], s[0:1], s[2:3]
	s_andn2_b64 vcc, exec, s[0:1]
	s_cbranch_vccnz .LBB0_117
	v_cmp_le_u32_e32 vcc, 0x100, v208
	s_cbranch_vccz .Lprio_skip0
	s_setprio 1
.Lprio_skip0:
	s_cmpk_gt_i32 s76, 0x5e7
	s_cbranch_scc1 .LBB0_63
	v_and_b32_e32 v11, 63, v208
	s_add_u32 s1, s94, 0xa20000
	v_lshlrev_b32_e32 v6, 2, v11
	s_addc_u32 s2, s95, 0
	v_lshrrev_b32_e32 v10, 6, v208
	v_lshl_or_b32 v0, v11, 8, v6
	v_and_b32_e32 v28, 15, v208
	v_lshrrev_b32_e32 v29, 4, v208
	s_add_u32 s10, s94, 0x9a0000
	v_lshl_add_u32 v27, v10, 2, v0
	v_mul_u32_u24_e32 v1, 0xc0, v29
	v_lshlrev_b32_e32 v0, 2, v28
	s_addc_u32 s11, s95, 0
	v_or_b32_e32 v30, v0, v1
	v_mul_u32_u24_e32 v1, 0xc00, v29
	s_load_dword s0, s[78:79], 0xd8
	s_add_u32 s12, s94, 0x910000
	v_or_b32_e32 v31, v1, v28
	s_addc_u32 s13, s95, 0
	v_lshrrev_b32_e32 v1, 9, v208
	s_add_u32 s14, s94, 0x710000
	v_sub_u32_e32 v1, 0, v1
	v_lshlrev_b32_e32 v8, 6, v29
	s_addc_u32 s15, s95, 0
	v_and_b32_e32 v32, 7, v1
	v_mul_u32_u24_e32 v2, 0x3000, v29
	v_mov_b32_e32 v1, 0
	v_mul_u32_u24_e32 v7, 0x104, v10
	v_add_u32_e32 v13, 8, v10
	v_or_b32_e32 v15, 16, v10
	v_add_u32_e32 v17, 24, v10
	v_or_b32_e32 v19, 32, v10
	v_add_u32_e32 v21, 40, v10
	v_or_b32_e32 v23, 48, v10
	v_add_u32_e32 v25, 56, v10
	s_add_u32 s16, s94, 0x10000
	v_mul_hi_u32_u24_e32 v3, 0x3000, v29
	v_or_b32_e32 v2, v2, v0
	v_lshl_add_u64 v[4:5], s[68:69], 0, v[0:1]
	s_mov_b64 s[8:9], 0x180000
	v_add_u32_e32 v0, v0, v8
	v_lshlrev_b32_e32 v12, 9, v10
	v_lshlrev_b32_e32 v14, 9, v13
	v_lshlrev_b32_e32 v16, 9, v15
	v_lshlrev_b32_e32 v18, 9, v17
	v_lshlrev_b32_e32 v20, 9, v19
	v_lshlrev_b32_e32 v22, 9, v21
	v_lshlrev_b32_e32 v24, 9, v23
	v_lshlrev_b32_e32 v26, 9, v25
	v_cmp_gt_u32_e64 s[4:5], 48, v208
	s_addc_u32 s17, s95, 0
	s_mov_b32 s19, 0
	v_cmp_ne_u32_e64 s[6:7], 0, v32
	v_lshlrev_b32_e32 v33, 2, v208
	v_lshlrev_b32_e32 v34, 2, v29
	s_movk_i32 s3, 0x3000
	v_lshl_add_u64 v[2:3], s[68:69], 0, v[2:3]
	s_lshl_b32 s20, s76, 4
	s_waitcnt lgkmcnt(0)
	s_lshl_b32 s30, s0, 4
	v_lshl_add_u64 v[4:5], v[4:5], 0, s[8:9]
	v_add_u32_e32 v35, v6, v7
	v_lshlrev_b32_e32 v36, 1, v11
	s_movk_i32 s31, 0xd9f
	s_movk_i32 s33, 0xda0
	s_movk_i32 s34, 0x400
	s_movk_i32 s35, 0x9ff
	s_mov_b64 s[22:23], 0x60000
	s_mov_b32 s36, 0x60000
	s_mov_b32 s37, 0xc0000
	s_mov_b32 s38, 0x120000
	s_mov_b64 s[24:25], 0x300000
	s_movk_i32 s39, 0x2ff
	v_add_u32_e32 v37, 0x4000, v30
	v_add_u32_e32 v38, 0x4000, v0
	v_add_u32_e32 v39, 0x4400, v0
	v_add_u32_e32 v40, 0x4600, v0
	v_add_u32_e32 v41, 0x4800, v0
	v_add_u32_e32 v42, 0x4c00, v0
	v_add_u32_e32 v43, 0x5000, v0
	v_add_u32_e32 v44, 0x5200, v0
	v_add_u32_e32 v45, 0x5400, v0
	s_mov_b32 s40, s76
	s_branch .LBB0_22
